# phase_final: the final y rows are stored with the nt (streaming) hint
# baseline (speedup 1.0000x reference)
; DI float bf_lo(unsigned u) { return __uint_as_float(u << 16); }
; DI float bf_hi(unsigned u) { return __uint_as_float(u & 0xffff0000u); }
; DI void phase_final(KP P) {
;     ...
;         for (int i = 0; i < 4; ++i) { const u32x2 wv = *(const u32x2*)(P->f + (long)row * DM + i * 256 + lane * 4);
;             fv[i] = (f32x4){bf_lo(wv.x), bf_hi(wv.x), bf_lo(wv.y), bf_hi(wv.y)}; s += fv[i][0] * fv[i][0] + fv[i][1] * fv[i][1] + fv[i][2] * fv[i][2] + fv[i][3] * fv[i][3]; }
; #pragma unroll
;         for (int o = 1; o < 64; o <<= 1) s += __shfl_xor(s, o);
;         const float rstd = rsqrtf(s * (1.0f / DM) + EPS);
; #pragma unroll
;         for (int i = 0; i < 4; ++i) { const int c = i * 256 + lane * 4; float* yp = P->out + O_Y + (long)row * DM + c;
;             const f32x4 xv = *(const f32x4*)yp, g = *(const f32x4*)(P->g_post_ffn + c), gt = *(const f32x4*)(ad + 5120 + c);
;             *(f32x4*)yp = xv + gt * (fv[i] * rstd * g); }
.Lpf_nonext:
	v_lshlrev_b32_e32 v104, 16, v24
	v_and_b32_e32 v105, 0xffff0000, v24
	v_lshlrev_b32_e32 v106, 16, v25
	v_and_b32_e32 v107, 0xffff0000, v25
	v_lshlrev_b32_e32 v108, 16, v26
	v_and_b32_e32 v109, 0xffff0000, v26
	v_lshlrev_b32_e32 v110, 16, v27
	v_and_b32_e32 v111, 0xffff0000, v27
	v_lshlrev_b32_e32 v112, 16, v28
	v_and_b32_e32 v113, 0xffff0000, v28
	v_lshlrev_b32_e32 v114, 16, v29
	v_and_b32_e32 v115, 0xffff0000, v29
	v_lshlrev_b32_e32 v116, 16, v30
	v_and_b32_e32 v117, 0xffff0000, v30
	v_lshlrev_b32_e32 v118, 16, v31
	v_and_b32_e32 v119, 0xffff0000, v31
	v_mul_f32_e32 v120, v104, v104
	v_mul_f32_e32 v121, v105, v105
	v_fmac_f32_e32 v120, v106, v106
	v_fmac_f32_e32 v121, v107, v107
	v_fmac_f32_e32 v120, v108, v108
	v_fmac_f32_e32 v121, v109, v109
	v_fmac_f32_e32 v120, v110, v110
	v_fmac_f32_e32 v121, v111, v111
	v_fmac_f32_e32 v120, v112, v112
	v_fmac_f32_e32 v121, v113, v113
	v_fmac_f32_e32 v120, v114, v114
	v_fmac_f32_e32 v121, v115, v115
	v_fmac_f32_e32 v120, v116, v116
	v_fmac_f32_e32 v121, v117, v117
	v_fmac_f32_e32 v120, v118, v118
	v_fmac_f32_e32 v121, v119, v119
	v_add_f32_e32 v120, v120, v121
	s_nop 1
	v_mov_b32_dpp v121, v120 quad_perm:[1,0,3,2] row_mask:0xf bank_mask:0xf bound_ctrl:1
	v_add_f32_e32 v120, v120, v121
	s_nop 1
	v_mov_b32_dpp v121, v120 quad_perm:[2,3,0,1] row_mask:0xf bank_mask:0xf bound_ctrl:1
	v_add_f32_e32 v120, v120, v121
	s_nop 1
	v_mov_b32_dpp v121, v120 row_ror:4 row_mask:0xf bank_mask:0xf bound_ctrl:1
	v_add_f32_e32 v120, v120, v121
	s_nop 1
	v_mov_b32_dpp v121, v120 row_ror:8 row_mask:0xf bank_mask:0xf bound_ctrl:1
	v_add_f32_e32 v120, v120, v121
	ds_bpermute_b32 v121, v6, v120
	s_waitcnt lgkmcnt(0)
	v_add_f32_e32 v120, v120, v121
	ds_bpermute_b32 v121, v7, v120
	s_waitcnt lgkmcnt(0)
	v_add_f32_e32 v120, v120, v121
	v_mov_b32_e32 v122, 0x358637bd
	v_fmamk_f32 v120, v120, 0x3a800000, v122
	v_rsq_f32_e32 v120, v120
	s_lshl_b32 s24, s18, 12
	s_add_u32 s20, s12, s24
	s_addc_u32 s21, s13, 0
	v_pk_mul_f32 v[104:105], v[104:105], v[120:121] op_sel_hi:[1,0]
	v_pk_mul_f32 v[106:107], v[106:107], v[120:121] op_sel_hi:[1,0]
	v_pk_mul_f32 v[104:105], v[104:105], v[8:9]
	v_pk_mul_f32 v[106:107], v[106:107], v[10:11]
	v_pk_fma_f32 v[104:105], v[48:49], v[104:105], v[32:33]
	v_pk_fma_f32 v[106:107], v[50:51], v[106:107], v[34:35]
	global_store_dwordx4 v0, v[104:107], s[20:21] nt
	v_pk_mul_f32 v[108:109], v[108:109], v[120:121] op_sel_hi:[1,0]
	v_pk_mul_f32 v[110:111], v[110:111], v[120:121] op_sel_hi:[1,0]
	v_pk_mul_f32 v[108:109], v[108:109], v[12:13]
	v_pk_mul_f32 v[110:111], v[110:111], v[14:15]
	v_pk_fma_f32 v[108:109], v[52:53], v[108:109], v[36:37]
	v_pk_fma_f32 v[110:111], v[54:55], v[110:111], v[38:39]
	global_store_dwordx4 v0, v[108:111], s[20:21] offset:1024 nt
	v_pk_mul_f32 v[112:113], v[112:113], v[120:121] op_sel_hi:[1,0]
	v_pk_mul_f32 v[114:115], v[114:115], v[120:121] op_sel_hi:[1,0]
	v_pk_mul_f32 v[112:113], v[112:113], v[16:17]
	v_pk_mul_f32 v[114:115], v[114:115], v[18:19]
	v_pk_fma_f32 v[112:113], v[56:57], v[112:113], v[40:41]
	v_pk_fma_f32 v[114:115], v[58:59], v[114:115], v[42:43]
	global_store_dwordx4 v0, v[112:115], s[20:21] offset:2048 nt
	v_pk_mul_f32 v[116:117], v[116:117], v[120:121] op_sel_hi:[1,0]
	v_pk_mul_f32 v[118:119], v[118:119], v[120:121] op_sel_hi:[1,0]
	v_pk_mul_f32 v[116:117], v[116:117], v[20:21]
	v_pk_mul_f32 v[118:119], v[118:119], v[22:23]
	v_pk_fma_f32 v[116:117], v[60:61], v[116:117], v[44:45]
	v_pk_fma_f32 v[118:119], v[62:63], v[118:119], v[46:47]
	global_store_dwordx4 v0, v[116:119], s[20:21] offset:3072 nt
	s_mov_b32 s18, s27
	s_cmpk_lt_i32 s18, 0x4100
	s_cbranch_scc1 .Lpf_loop
